# v022: conv_item_p staging rewritten wave-uniform: 14 row loads in flight with scalar addresses, next item's loads issued before compute of current item (cross-item prefetch), redundant vmcnt(0) waits
# speedup vs baseline: 1.0093x; 1.0093x over previous
.LBB0_434:
	s_or_b32 s55, s54, s44
	s_lshl_b32 s33, s55, 4
	s_mov_b64 s[14:15], s[42:43]
	s_mov_b64 s[94:95], s[42:43]
	s_add_u32 s30, s14, 0x18400000
	s_mov_b64 s[92:93], s[40:41]
	s_mov_b64 s[90:91], s[38:39]
	s_mov_b64 s[88:89], s[36:37]
	s_addc_u32 s31, s15, 0
	s_cmp_lg_u32 s54, 0
	s_cbranch_scc1 .Lcp_wait6
	s_mov_b32 s17, s33
	s_mov_b32 s18, 0
	s_branch .Lcp_issue
.Lcp_first_back:
	s_waitcnt vmcnt(0)
	s_branch .Lcp_write
.Lcp_wait6:
	s_waitcnt vmcnt(6)
.Lcp_write:
	s_lshr_b32 s16, s64, 6
	v_lshl_add_u32 v190, s16, 10, v83
	v_add_u32_e32 v191, 0x10000, v190
	ds_write_b128 v190, v[124:127]
	ds_write_b128 v190, v[128:131] offset:8192
	ds_write_b128 v190, v[132:135] offset:16384
	ds_write_b128 v190, v[136:139] offset:24576
	ds_write_b128 v190, v[166:169] offset:32768
	ds_write_b128 v190, v[170:173] offset:40960
	ds_write_b128 v190, v[174:177] offset:49152
	ds_write_b128 v190, v[178:181] offset:57344
	ds_write_b128 v191, v[182:185]
	ds_write_b128 v191, v[186:189] offset:8192
	ds_write_b128 v191, v[204:207] offset:16384
	ds_write_b128 v191, v[208:211] offset:24576
	ds_write_b128 v191, v[230:233] offset:32768
	s_cmp_eq_u32 s16, 7
	s_cbranch_scc1 .Lcp_w13
	ds_write_b128 v191, v[242:245] offset:40960
.Lcp_w13:
	s_cmp_eq_u32 s54, 3
	s_cbranch_scc1 .Lcp_noissue
	s_add_i32 s17, s33, 16
	s_mov_b32 s18, 1
.Lcp_issue:
	s_lshr_b32 s16, s64, 6
	s_add_i32 s19, s17, s16
	s_add_i32 s22, s19, s45
	s_mul_i32 s28, s22, s76
	s_add_u32 s28, s28, s30
	s_addc_u32 s29, s31, 0
	s_add_i32 s22, s19, -15
	s_cmp_lt_i32 s22, 0
	s_cbranch_scc1 .Lcp_z0
	s_add_u32 s24, s28, 0xfffcb800
	s_addc_u32 s25, s29, -1
	global_load_dwordx4 v[124:127], v83, s[24:25]
	s_branch .Lcp_n0
.Lcp_z0:
	v_mov_b32_e32 v124, 0
	v_mov_b32_e32 v125, 0
	v_mov_b32_e32 v126, 0
	v_mov_b32_e32 v127, 0
.Lcp_n0:
	s_add_i32 s22, s19, -7
	s_cmp_lt_i32 s22, 0
	s_cbranch_scc1 .Lcp_z1
	s_add_u32 s24, s28, 0xfffe7800
	s_addc_u32 s25, s29, -1
	global_load_dwordx4 v[128:131], v83, s[24:25]
	s_branch .Lcp_n1
.Lcp_z1:
	v_mov_b32_e32 v128, 0
	v_mov_b32_e32 v129, 0
	v_mov_b32_e32 v130, 0
	v_mov_b32_e32 v131, 0
.Lcp_n1:
	s_add_u32 s24, s28, 0x3800
	s_addc_u32 s25, s29, 0
	global_load_dwordx4 v[132:135], v83, s[24:25]
.Lcp_n2:
	s_mov_b32 s21, 0x1f800
	s_mov_b32 s23, 0
	s_mov_b32 s20, 9
	s_cmp_eq_u32 s16, 7
	s_cselect_b32 s21, 0xfffe0c00, s21
	s_cselect_b32 s23, -1, s23
	s_cselect_b32 s20, -9, s20
	s_add_i32 s22, s19, s20
	s_cmp_lt_i32 s22, 0
	s_cbranch_scc1 .Lcp_z3
	s_add_u32 s24, s28, s21
	s_addc_u32 s25, s29, s23
	global_load_dwordx4 v[136:139], v83, s[24:25]
	s_branch .Lcp_n3
.Lcp_z3:
	v_mov_b32_e32 v136, 0
	v_mov_b32_e32 v137, 0
	v_mov_b32_e32 v138, 0
	v_mov_b32_e32 v139, 0
.Lcp_n3:
	s_add_i32 s22, s19, -1
	s_cmp_lt_i32 s22, 0
	s_cbranch_scc1 .Lcp_z4
	s_add_u32 s24, s28, 0xffffcc00
	s_addc_u32 s25, s29, -1
	global_load_dwordx4 v[166:169], v83, s[24:25]
	s_branch .Lcp_n4
.Lcp_z4:
	v_mov_b32_e32 v166, 0
	v_mov_b32_e32 v167, 0
	v_mov_b32_e32 v168, 0
	v_mov_b32_e32 v169, 0
.Lcp_n4:
	s_add_u32 s24, s28, 0x18c00
	s_addc_u32 s25, s29, 0
	global_load_dwordx4 v[170:173], v83, s[24:25]
.Lcp_n5:
	s_mov_b32 s21, 0xffffd000
	s_mov_b32 s23, -1
	s_mov_b32 s20, -1
	s_cmp_eq_u32 s16, 0
	s_cselect_b32 s21, 0x34c00, s21
	s_cselect_b32 s23, 0, s23
	s_cselect_b32 s20, 15, s20
	s_add_i32 s22, s19, s20
	s_cmp_lt_i32 s22, 0
	s_cbranch_scc1 .Lcp_z6
	s_add_u32 s24, s28, s21
	s_addc_u32 s25, s29, s23
	global_load_dwordx4 v[174:177], v83, s[24:25]
	s_branch .Lcp_n6
.Lcp_z6:
	v_mov_b32_e32 v174, 0
	v_mov_b32_e32 v175, 0
	v_mov_b32_e32 v176, 0
	v_mov_b32_e32 v177, 0
.Lcp_n6:
	s_add_u32 s24, s28, 0x19000
	s_addc_u32 s25, s29, 0
	global_load_dwordx4 v[178:181], v83, s[24:25]
.Lcp_n7:
	s_mov_b32 s21, 0xfff94c00
	s_mov_b32 s23, -1
	s_mov_b32 s20, 0xffffffe1
	s_cmp_eq_u32 s16, 0
	s_cselect_b32 s21, 0x35000, s21
	s_cselect_b32 s23, 0, s23
	s_cselect_b32 s20, 15, s20
	s_add_i32 s22, s19, s20
	s_cmp_lt_i32 s22, 0
	s_cbranch_scc1 .Lcp_z8
	s_add_u32 s24, s28, s21
	s_addc_u32 s25, s29, s23
	global_load_dwordx4 v[182:185], v83, s[24:25]
	s_branch .Lcp_n8
.Lcp_z8:
	v_mov_b32_e32 v182, 0
	v_mov_b32_e32 v183, 0
	v_mov_b32_e32 v184, 0
	v_mov_b32_e32 v185, 0
.Lcp_n8:
	s_add_i32 s22, s19, 0xffffffe9
	s_cmp_lt_i32 s22, 0
	s_cbranch_scc1 .Lcp_z9
	s_add_u32 s24, s28, 0xfffb0c00
	s_addc_u32 s25, s29, -1
	global_load_dwordx4 v[186:189], v83, s[24:25]
	s_branch .Lcp_n9
.Lcp_z9:
	v_mov_b32_e32 v186, 0
	v_mov_b32_e32 v187, 0
	v_mov_b32_e32 v188, 0
	v_mov_b32_e32 v189, 0
.Lcp_n9:
	s_add_i32 s22, s19, -15
	s_cmp_lt_i32 s22, 0
	s_cbranch_scc1 .Lcp_z10
	s_add_u32 s24, s28, 0xfffccc00
	s_addc_u32 s25, s29, -1
	global_load_dwordx4 v[204:207], v83, s[24:25]
	s_branch .Lcp_n10
.Lcp_z10:
	v_mov_b32_e32 v204, 0
	v_mov_b32_e32 v205, 0
	v_mov_b32_e32 v206, 0
	v_mov_b32_e32 v207, 0
.Lcp_n10:
	s_add_i32 s22, s19, -7
	s_cmp_lt_i32 s22, 0
	s_cbranch_scc1 .Lcp_z11
	s_add_u32 s24, s28, 0xfffe8c00
	s_addc_u32 s25, s29, -1
	global_load_dwordx4 v[208:211], v83, s[24:25]
	s_branch .Lcp_n11
.Lcp_z11:
	v_mov_b32_e32 v208, 0
	v_mov_b32_e32 v209, 0
	v_mov_b32_e32 v210, 0
	v_mov_b32_e32 v211, 0
.Lcp_n11:
	s_add_u32 s24, s28, 0x4c00
	s_addc_u32 s25, s29, 0
	global_load_dwordx4 v[230:233], v83, s[24:25]
.Lcp_n12:
	s_cmp_eq_u32 s16, 7
	s_cbranch_scc1 .Lcp_n13
	s_add_u32 s24, s28, 0x20c00
	s_addc_u32 s25, s29, 0
	global_load_dwordx4 v[242:245], v83, s[24:25]
.Lcp_n13:
	s_cmp_eq_u32 s18, 0
	s_cbranch_scc1 .Lcp_first_back
.Lcp_noissue:
.LBB0_548:
	s_cmpk_gt_u32 s55, 0x7e
	s_cselect_b64 s[14:15], -1, 0
	s_and_b64 s[14:15], s[0:1], s[14:15]
	s_waitcnt lgkmcnt(0)
	s_barrier
	s_and_saveexec_b64 s[20:21], s[14:15]
	s_mov_b64 s[36:37], s[88:89]
	s_mov_b64 s[38:39], s[90:91]
	s_mov_b64 s[40:41], s[92:93]
	s_mov_b64 s[42:43], s[94:95]
	s_cbranch_execz .LBB0_553
	s_mov_b64 s[22:23], 0
	s_waitcnt vmcnt(0)
	v_mov_b32_e32 v0, v84
	v_mov_b32_e32 v1, v64
	s_branch .LBB0_551

.LBB0_553:
	s_or_b64 exec, exec, s[20:21]
	s_mov_b64 s[18:19], -1
	s_mov_b64 s[14:15], 0
	s_cmp_lt_i32 s2, 1
	s_mov_b64 s[16:17], 0
	s_cbranch_scc1 .LBB0_558
	s_cmp_gt_i32 s2, 1
	s_cbranch_scc0 .LBB0_564
	s_cmp_eq_u32 s2, 2
	s_mov_b64 s[16:17], -1
	s_cbranch_scc0 .LBB0_557
	ds_read_u16 v0, v86 offset:16384
	ds_read_u16 v2, v86 offset:17408
	ds_read_u16 v3, v86 offset:18432
	ds_read_u16 v4, v86 offset:19456
	ds_read_u16 v5, v86 offset:20480
	ds_read_u16 v43, v86 offset:23552
	ds_read_u16 v45, v86 offset:22528
	ds_read_u16 v47, v86 offset:21504
	s_waitcnt lgkmcnt(0)
	v_lshlrev_b32_e32 v1, 16, v0
	ds_read_u16 v0, v86 offset:8192
	ds_read_u16 v7, v86 offset:9216
	ds_read_u16 v8, v86 offset:10240
	ds_read_u16 v10, v86 offset:11264
	ds_read_u16 v11, v86 offset:12288
	ds_read_u16 v14, v86 offset:13312
	ds_read_u16 v16, v86 offset:14336
	ds_read_u16 v18, v86 offset:15360
	s_waitcnt lgkmcnt(7)
	v_lshlrev_b32_e32 v6, 16, v0
	s_waitcnt lgkmcnt(3)
	v_lshlrev_b32_e32 v11, 16, v11
	s_waitcnt lgkmcnt(2)
	v_lshlrev_b32_e32 v15, 16, v14
	s_waitcnt lgkmcnt(1)
	v_lshlrev_b32_e32 v17, 16, v16
	s_waitcnt lgkmcnt(0)
	v_lshlrev_b32_e32 v19, 16, v18
	v_mov_b32_e32 v0, v19
	v_mov_b32_e32 v18, v17
	v_pk_add_f32 v[20:21], v[0:1], 0 op_sel_hi:[1,0]
	v_mov_b32_e32 v16, v15
	v_pk_add_f32 v[20:21], v[20:21], v[18:19]
	v_mov_b32_e32 v14, v11
	v_pk_add_f32 v[20:21], v[20:21], v[16:17]
	v_lshlrev_b32_e32 v9, 16, v8
	v_lshlrev_b32_e32 v10, 16, v10
	v_pk_add_f32 v[20:21], v[20:21], v[14:15]
	v_lshlrev_b32_e32 v7, 16, v7
	v_mov_b32_e32 v12, v9
	v_mov_b32_e32 v13, v10
	v_pk_add_f32 v[20:21], v[20:21], v[10:11]
	v_lshlrev_b32_e32 v2, 16, v2
	v_lshlrev_b32_e32 v3, 16, v3
	v_mov_b32_e32 v8, v7
	v_pk_add_f32 v[20:21], v[20:21], v[12:13]
	v_pk_mov_b32 v[22:23], v[0:1], v[2:3] op_sel:[1,0]
	v_pk_add_f32 v[8:9], v[20:21], v[8:9]
	v_pk_add_f32 v[20:21], v[2:3], 0 op_sel_hi:[1,0]
	v_lshlrev_b32_e32 v4, 16, v4
	v_pk_add_f32 v[20:21], v[20:21], v[22:23]
	v_lshlrev_b32_e32 v5, 16, v5
	v_pk_add_f32 v[20:21], v[20:21], v[0:1]
	v_pk_add_f32 v[56:57], v[4:5], 0 op_sel_hi:[1,0]
	v_pk_add_f32 v[20:21], v[20:21], v[18:19]
	v_pk_mov_b32 v[58:59], v[2:3], v[4:5] op_sel:[1,0]
	v_pk_add_f32 v[20:21], v[20:21], v[16:17]
	v_pk_add_f32 v[56:57], v[56:57], v[58:59]
	v_pk_add_f32 v[20:21], v[20:21], v[14:15]
	v_pk_add_f32 v[56:57], v[56:57], v[2:3]
	v_pk_add_f32 v[10:11], v[20:21], v[10:11]
	ds_read_u16 v20, v86 offset:29696
	ds_read_u16 v21, v86 offset:30720
	ds_read_u16 v24, v86 offset:28672
	ds_read_u16 v26, v86 offset:27648
	ds_read_u16 v27, v86 offset:26624
	ds_read_u16 v49, v86 offset:25600
	ds_read_u16 v50, v86 offset:24576
	v_pk_add_f32 v[56:57], v[56:57], v[22:23]
	v_lshlrev_b32_e32 v53, 16, v45
	v_lshlrev_b32_e32 v52, 16, v47
	v_pk_add_f32 v[56:57], v[56:57], v[0:1]
	s_waitcnt lgkmcnt(0)
	v_lshlrev_b32_e32 v51, 16, v50
	v_lshlrev_b32_e32 v50, 16, v43
	v_pk_add_f32 v[56:57], v[56:57], v[18:19]
	v_pk_add_f32 v[76:77], v[50:51], 0 op_sel_hi:[1,0]
	v_pk_mov_b32 v[78:79], v[52:53], v[50:51] op_sel:[1,0]
	v_pk_add_f32 v[16:17], v[56:57], v[16:17]
	v_pk_add_f32 v[76:77], v[76:77], v[78:79]
	v_pk_add_f32 v[14:15], v[16:17], v[14:15]
	v_pk_add_f32 v[16:17], v[52:53], 0 op_sel_hi:[1,0]
	v_pk_mov_b32 v[56:57], v[4:5], v[52:53] op_sel:[1,0]
	v_pk_add_f32 v[76:77], v[76:77], v[52:53]
	v_pk_add_f32 v[16:17], v[16:17], v[56:57]
	v_pk_add_f32 v[76:77], v[76:77], v[56:57]
	v_pk_add_f32 v[16:17], v[16:17], v[4:5]
	v_pk_add_f32 v[76:77], v[76:77], v[4:5]
	v_pk_add_f32 v[16:17], v[16:17], v[58:59]
	v_pk_add_f32 v[76:77], v[76:77], v[58:59]
	v_lshlrev_b32_e32 v25, 16, v24
	v_lshlrev_b32_e32 v24, 16, v26
	v_lshlrev_b32_e32 v27, 16, v27
	v_lshlrev_b32_e32 v26, 16, v49
	v_pk_add_f32 v[16:17], v[16:17], v[2:3]
	v_pk_add_f32 v[76:77], v[76:77], v[2:3]
	v_pk_add_f32 v[16:17], v[16:17], v[22:23]
	v_pk_add_f32 v[22:23], v[76:77], v[22:23]
	v_pk_add_f32 v[76:77], v[26:27], 0 op_sel_hi:[1,0]
	v_pk_mov_b32 v[80:81], v[50:51], v[26:27] op_sel:[1,0]
	v_pk_mov_b32 v[98:99], v[26:27], v[24:25] op_sel:[1,0]
	v_pk_add_f32 v[76:77], v[76:77], v[80:81]
	v_lshlrev_b32_e32 v20, 16, v20
	v_pk_add_f32 v[76:77], v[76:77], v[50:51]
	v_lshlrev_b32_e32 v21, 16, v21
	v_pk_add_f32 v[76:77], v[76:77], v[78:79]
	v_pk_mov_b32 v[100:101], v[24:25], v[20:21] op_sel:[1,0]
	v_pk_add_f32 v[76:77], v[76:77], v[52:53]
	s_cmp_eq_u32 s55, 0
	v_pk_add_f32 v[76:77], v[76:77], v[56:57]
	s_cselect_b64 vcc, -1, 0
	v_pk_add_f32 v[76:77], v[76:77], v[4:5]
	v_pk_add_f32 v[16:17], v[16:17], v[0:1]
	v_pk_add_f32 v[58:59], v[76:77], v[58:59]
	v_pk_add_f32 v[76:77], v[24:25], 0 op_sel_hi:[1,0]
	v_pk_add_f32 v[6:7], v[8:9], v[6:7]
	v_pk_add_f32 v[76:77], v[76:77], v[98:99]
	v_cndmask_b32_e64 v9, v199, 0.5, vcc
	v_pk_add_f32 v[76:77], v[76:77], v[26:27]
	v_cndmask_b32_e64 v8, v199, 1.0, vcc
	v_pk_add_f32 v[76:77], v[76:77], v[80:81]
	v_pk_add_f32 v[10:11], v[10:11], v[12:13]
	v_pk_add_f32 v[76:77], v[76:77], v[50:51]
	v_cndmask_b32_e32 v13, v199, v201, vcc
	v_pk_add_f32 v[76:77], v[76:77], v[78:79]
	v_cndmask_b32_e32 v12, v199, v226, vcc
	v_pk_add_f32 v[76:77], v[76:77], v[52:53]
	v_cndmask_b32_e32 v55, v199, v227, vcc
	v_pk_add_f32 v[56:57], v[76:77], v[56:57]
	v_pk_add_f32 v[76:77], v[20:21], 0 op_sel_hi:[1,0]
	v_cndmask_b32_e32 v54, v199, v228, vcc
	v_pk_add_f32 v[76:77], v[76:77], v[100:101]
	v_cndmask_b32_e32 v198, v199, v229, vcc
	v_pk_add_f32 v[76:77], v[76:77], v[24:25]
	v_pk_add_f32 v[16:17], v[16:17], v[18:19]
	v_pk_add_f32 v[76:77], v[76:77], v[98:99]
	s_mov_b32 s16, 0x3e000000
	v_pk_add_f32 v[76:77], v[76:77], v[26:27]
	v_pk_mul_f32 v[6:7], v[8:9], v[6:7]
	v_pk_add_f32 v[76:77], v[76:77], v[80:81]
	v_pk_mul_f32 v[8:9], v[12:13], v[10:11]
	v_pk_add_f32 v[76:77], v[76:77], v[50:51]
	v_pk_mul_f32 v[10:11], v[54:55], v[14:15]
	v_pk_add_f32 v[76:77], v[76:77], v[78:79]
	v_pk_mul_f32 v[16:17], v[198:199], v[16:17]
	v_pk_mul_f32 v[54:55], v[76:77], s[16:17] op_sel_hi:[1,0]
	v_pk_mul_f32 v[56:57], v[56:57], s[16:17] op_sel_hi:[1,0]
	v_pk_mul_f32 v[58:59], v[58:59], s[16:17] op_sel_hi:[1,0]
	v_pk_mul_f32 v[22:23], v[22:23], s[16:17] op_sel_hi:[1,0]
	v_sub_f32_e32 v12, v8, v2
	v_sub_f32_e32 v13, v9, v3
	v_sub_f32_e32 v4, v10, v4
	v_sub_f32_e32 v5, v11, v5
	v_sub_f32_e32 v14, v6, v19
	v_sub_f32_e32 v15, v7, v1
	v_sub_f32_e32 v0, v16, v52
	v_sub_f32_e32 v1, v17, v53
	v_sub_f32_e32 v10, v22, v50
	v_sub_f32_e32 v11, v23, v51
	v_sub_f32_e32 v8, v58, v26
	v_sub_f32_e32 v9, v59, v27
	v_sub_f32_e32 v2, v56, v24
	v_sub_f32_e32 v3, v57, v25
	v_sub_f32_e32 v6, v54, v20
	v_sub_f32_e32 v7, v55, v21
	s_mov_b64 s[16:17], 0

.LBB0_561:
	ds_read_u16 v0, v86 offset:14336
	ds_read_u16 v1, v86 offset:15360
	ds_read_u16 v2, v86 offset:16384
	ds_read_u16 v6, v86 offset:17408
	ds_read_u16 v7, v86 offset:18432
	ds_read_u16 v12, v86 offset:19456
	ds_read_u16 v13, v86 offset:20480
	ds_read_u16 v16, v86 offset:21504
	s_waitcnt lgkmcnt(0)
	v_lshlrev_b32_e32 v1, 16, v1
	v_lshlrev_b32_e32 v3, 16, v2
	v_mov_b32_e32 v2, v1
	v_lshlrev_b32_e32 v7, 16, v7
	v_lshlrev_b32_e32 v6, 16, v6
	v_pk_add_f32 v[8:9], v[6:7], 0 op_sel_hi:[1,0]
	v_pk_mov_b32 v[10:11], v[2:3], v[6:7] op_sel:[1,0]
	v_lshlrev_b32_e32 v0, 16, v0
	v_pk_add_f32 v[4:5], v[2:3], 0 op_sel_hi:[1,0]
	v_pk_add_f32 v[8:9], v[8:9], v[10:11]
	v_lshlrev_b32_e32 v11, 16, v13
	v_lshlrev_b32_e32 v10, 16, v12
	v_pk_add_f32 v[4:5], v[4:5], v[0:1]
	v_pk_add_f32 v[12:13], v[10:11], 0 op_sel_hi:[1,0]
	v_pk_mov_b32 v[14:15], v[6:7], v[10:11] op_sel:[1,0]
	ds_read_u16 v0, v86 offset:22528
	ds_read_u16 v2, v86 offset:23552
	ds_read_u16 v20, v86 offset:24576
	ds_read_u16 v24, v86 offset:25600
	ds_read_u16 v25, v86 offset:26624
	ds_read_u16 v43, v86 offset:27648
	ds_read_u16 v45, v86 offset:28672
	ds_read_u16 v47, v86 offset:29696
	s_waitcnt lgkmcnt(7)
	v_lshlrev_b32_e32 v17, 16, v0
	v_lshlrev_b32_e32 v16, 16, v16
	v_pk_add_f32 v[12:13], v[12:13], v[14:15]
	v_pk_add_f32 v[14:15], v[16:17], 0 op_sel_hi:[1,0]
	v_pk_mov_b32 v[18:19], v[10:11], v[16:17] op_sel:[1,0]
	ds_read_u16 v0, v86 offset:30720
	v_pk_add_f32 v[14:15], v[14:15], v[18:19]
	s_waitcnt lgkmcnt(6)
	v_lshlrev_b32_e32 v19, 16, v20
	v_lshlrev_b32_e32 v18, 16, v2
	v_pk_add_f32 v[20:21], v[18:19], 0 op_sel_hi:[1,0]
	v_pk_mov_b32 v[22:23], v[16:17], v[18:19] op_sel:[1,0]
	s_cmp_eq_u32 s55, 0
	v_pk_add_f32 v[20:21], v[20:21], v[22:23]
	s_waitcnt lgkmcnt(4)
	v_lshlrev_b32_e32 v23, 16, v25
	v_lshlrev_b32_e32 v22, 16, v24
	v_pk_add_f32 v[24:25], v[22:23], 0 op_sel_hi:[1,0]
	v_pk_mov_b32 v[26:27], v[18:19], v[22:23] op_sel:[1,0]
	s_cselect_b64 s[14:15], -1, 0
	v_pk_add_f32 v[24:25], v[24:25], v[26:27]
	s_waitcnt lgkmcnt(2)
	v_lshlrev_b32_e32 v27, 16, v45
	v_lshlrev_b32_e32 v26, 16, v43
	v_pk_add_f32 v[50:51], v[26:27], 0 op_sel_hi:[1,0]
	v_pk_mov_b32 v[52:53], v[22:23], v[26:27] op_sel:[1,0]
	v_cndmask_b32_e64 v194, 0.5, 1.0, s[14:15]
	v_pk_add_f32 v[50:51], v[50:51], v[52:53]
	s_waitcnt lgkmcnt(1)
	v_lshlrev_b32_e32 v52, 16, v47
	s_waitcnt lgkmcnt(0)
	v_lshlrev_b32_e32 v53, 16, v0
	v_pk_add_f32 v[54:55], v[52:53], 0 op_sel_hi:[1,0]
	v_pk_mov_b32 v[56:57], v[26:27], v[52:53] op_sel:[1,0]
	v_pk_mul_f32 v[4:5], v[194:195], v[4:5]
	v_pk_add_f32 v[54:55], v[54:55], v[56:57]
	v_pk_mul_f32 v[8:9], v[8:9], 0.5 op_sel_hi:[1,0]
	v_pk_mul_f32 v[56:57], v[14:15], 0.5 op_sel_hi:[1,0]
	v_pk_mul_f32 v[58:59], v[12:13], 0.5 op_sel_hi:[1,0]
	v_pk_mul_f32 v[54:55], v[54:55], 0.5 op_sel_hi:[1,0]
	v_pk_mul_f32 v[50:51], v[50:51], 0.5 op_sel_hi:[1,0]
	v_pk_mul_f32 v[24:25], v[24:25], 0.5 op_sel_hi:[1,0]
	v_pk_mul_f32 v[20:21], v[20:21], 0.5 op_sel_hi:[1,0]
	v_sub_f32_e32 v14, v4, v1
	v_sub_f32_e32 v15, v5, v3
	v_sub_f32_e32 v12, v8, v6
	v_sub_f32_e32 v13, v9, v7
	v_sub_f32_e32 v4, v58, v10
	v_sub_f32_e32 v5, v59, v11
	v_sub_f32_e32 v0, v56, v16
	v_sub_f32_e32 v1, v57, v17
	v_sub_f32_e32 v10, v20, v18
	v_sub_f32_e32 v11, v21, v19
	v_sub_f32_e32 v8, v24, v22
	v_sub_f32_e32 v9, v25, v23
	v_sub_f32_e32 v2, v50, v26
	v_sub_f32_e32 v3, v51, v27
	v_sub_f32_e32 v6, v54, v52
	v_sub_f32_e32 v7, v55, v53
.LBB0_562:
	ds_read_u16 v50, v86 offset:32768
	ds_read_u16 v51, v86 offset:33792
	ds_read_u16 v52, v86 offset:34816
	ds_read_u16 v53, v86 offset:35840
	ds_read_u16 v55, v86 offset:36864
	ds_read_u16 v56, v86 offset:37888
	ds_read_u16 v57, v86 offset:38912
	ds_read_u16 v58, v86 offset:39936
	ds_read_u16 v59, v86 offset:40960
	ds_read_u16 v77, v86 offset:41984
	ds_read_u16 v78, v86 offset:43008
	ds_read_u16 v79, v86 offset:44032
	ds_read_u16 v80, v86 offset:45056
	ds_read_u16 v76, v86 offset:46080
	ds_read_u16 v54, v86 offset:47104
	ds_read_u16 v81, v86 offset:48128
	ds_read_u16 v16, v89
	ds_read_u16 v17, v89 offset:1024
	ds_read_u16 v18, v89 offset:2048
	ds_read_u16 v19, v89 offset:3072
	ds_read_u16 v20, v89 offset:4096
	ds_read_u16 v21, v89 offset:5120
	ds_read_u16 v22, v89 offset:6144
	ds_read_u16 v23, v89 offset:7168
	s_waitcnt lgkmcnt(0)
	v_lshlrev_b32_e32 v16, 16, v16
	v_fma_f32 v49, v150, v16, v60
	v_lshlrev_b32_e32 v16, 16, v17
	v_fmac_f32_e32 v49, v149, v16
	v_fma_f32 v47, v150, v16, v60
	v_lshlrev_b32_e32 v16, 16, v18
	v_fmac_f32_e32 v49, v148, v16
	v_fmac_f32_e32 v47, v149, v16
	v_fma_f32 v45, v150, v16, v60
	v_lshlrev_b32_e32 v16, 16, v19
	v_fmac_f32_e32 v49, v147, v16
	v_fmac_f32_e32 v47, v148, v16
	v_fmac_f32_e32 v45, v149, v16
	v_fma_f32 v43, v150, v16, v60
	v_lshlrev_b32_e32 v16, 16, v20
	v_fmac_f32_e32 v49, v145, v16
	v_fmac_f32_e32 v47, v147, v16
	v_fmac_f32_e32 v45, v148, v16
	v_fmac_f32_e32 v43, v149, v16
	v_fma_f32 v27, v150, v16, v60
	v_lshlrev_b32_e32 v16, 16, v21
	v_fmac_f32_e32 v49, v61, v16
	v_fmac_f32_e32 v47, v145, v16
	v_fmac_f32_e32 v45, v147, v16
	v_fmac_f32_e32 v43, v148, v16
	v_fmac_f32_e32 v27, v149, v16
	v_fma_f32 v26, v150, v16, v60
	v_lshlrev_b32_e32 v16, 16, v22
	v_fmac_f32_e32 v49, v146, v16
	v_fmac_f32_e32 v47, v61, v16
	v_fmac_f32_e32 v45, v145, v16
	v_fmac_f32_e32 v43, v147, v16
	v_fmac_f32_e32 v27, v148, v16
	v_fmac_f32_e32 v26, v149, v16
	v_fma_f32 v25, v150, v16, v60
	v_lshlrev_b32_e32 v16, 16, v23
	v_fmac_f32_e32 v49, v144, v16
	v_fmac_f32_e32 v47, v146, v16
	v_fmac_f32_e32 v45, v61, v16
	v_fmac_f32_e32 v43, v145, v16
	v_fmac_f32_e32 v27, v147, v16
	v_fmac_f32_e32 v26, v148, v16
	v_fmac_f32_e32 v25, v149, v16
	v_fma_f32 v23, v150, v16, v60
	ds_read_u16 v16, v89 offset:8192
	ds_read_u16 v17, v89 offset:9216
	ds_read_u16 v18, v89 offset:10240
	ds_read_u16 v19, v89 offset:11264
	ds_read_u16 v98, v89 offset:12288
	ds_read_u16 v99, v89 offset:13312
	ds_read_u16 v100, v89 offset:14336
	ds_read_u16 v101, v89 offset:15360
	s_waitcnt lgkmcnt(7)
	v_lshlrev_b32_e32 v16, 16, v16
	v_fmac_f32_e32 v49, v158, v16
	v_fmac_f32_e32 v47, v144, v16
	v_fmac_f32_e32 v45, v146, v16
	v_fmac_f32_e32 v43, v61, v16
	v_fmac_f32_e32 v27, v145, v16
	v_fmac_f32_e32 v26, v147, v16
	v_fmac_f32_e32 v25, v148, v16
	v_fmac_f32_e32 v23, v149, v16
	v_fma_f32 v24, v150, v16, v60
	s_waitcnt lgkmcnt(6)
	v_lshlrev_b32_e32 v16, 16, v17
	v_fmac_f32_e32 v49, v157, v16
	v_fmac_f32_e32 v47, v158, v16
	v_fmac_f32_e32 v45, v144, v16
	v_fmac_f32_e32 v43, v146, v16
	v_fmac_f32_e32 v27, v61, v16
	v_fmac_f32_e32 v26, v145, v16
	v_fmac_f32_e32 v25, v147, v16
	v_fmac_f32_e32 v23, v148, v16
	v_fmac_f32_e32 v24, v149, v16
	v_fma_f32 v22, v150, v16, v60
	s_waitcnt lgkmcnt(5)
	v_lshlrev_b32_e32 v16, 16, v18
	v_fmac_f32_e32 v49, v156, v16
	v_fmac_f32_e32 v47, v157, v16
	v_fmac_f32_e32 v45, v158, v16
	v_fmac_f32_e32 v43, v144, v16
	v_fmac_f32_e32 v27, v146, v16
	v_fmac_f32_e32 v26, v61, v16
	v_fmac_f32_e32 v25, v145, v16
	v_fmac_f32_e32 v23, v147, v16
	v_fmac_f32_e32 v24, v148, v16
	v_fmac_f32_e32 v22, v149, v16
	v_fma_f32 v21, v150, v16, v60
	s_waitcnt lgkmcnt(4)
	v_lshlrev_b32_e32 v16, 16, v19
	v_fmac_f32_e32 v49, v155, v16
	v_fmac_f32_e32 v47, v156, v16
	v_fmac_f32_e32 v45, v157, v16
	v_fmac_f32_e32 v43, v158, v16
	v_fmac_f32_e32 v27, v144, v16
	v_fmac_f32_e32 v26, v146, v16
	v_fmac_f32_e32 v25, v61, v16
	v_fmac_f32_e32 v23, v145, v16
	v_fmac_f32_e32 v24, v147, v16
	v_fmac_f32_e32 v22, v148, v16
	v_fmac_f32_e32 v21, v149, v16
	v_fma_f32 v20, v150, v16, v60
	s_waitcnt lgkmcnt(3)
	v_lshlrev_b32_e32 v16, 16, v98
	v_fmac_f32_e32 v49, v153, v16
	v_fmac_f32_e32 v47, v155, v16
	v_fmac_f32_e32 v45, v156, v16
	v_fmac_f32_e32 v43, v157, v16
	v_fmac_f32_e32 v27, v158, v16
	v_fmac_f32_e32 v26, v144, v16
	v_fmac_f32_e32 v25, v146, v16
	v_fmac_f32_e32 v23, v61, v16
	v_fmac_f32_e32 v24, v145, v16
	v_fmac_f32_e32 v22, v147, v16
	v_fmac_f32_e32 v21, v148, v16
	v_fmac_f32_e32 v20, v149, v16
	v_fma_f32 v19, v150, v16, v60
	s_waitcnt lgkmcnt(2)
	v_lshlrev_b32_e32 v16, 16, v99
	v_fmac_f32_e32 v49, v151, v16
	v_fmac_f32_e32 v47, v153, v16
	v_fmac_f32_e32 v45, v155, v16
	v_fmac_f32_e32 v43, v156, v16
	v_fmac_f32_e32 v27, v157, v16
	v_fmac_f32_e32 v26, v158, v16
	v_fmac_f32_e32 v25, v144, v16
	v_fmac_f32_e32 v23, v146, v16
	v_fmac_f32_e32 v24, v61, v16
	v_fmac_f32_e32 v22, v145, v16
	v_fmac_f32_e32 v21, v147, v16
	v_fmac_f32_e32 v20, v148, v16
	v_fmac_f32_e32 v19, v149, v16
	v_fma_f32 v18, v150, v16, v60
	s_waitcnt lgkmcnt(1)
	v_lshlrev_b32_e32 v16, 16, v100
	v_fmac_f32_e32 v49, v154, v16
	v_fmac_f32_e32 v47, v151, v16
	v_fmac_f32_e32 v45, v153, v16
	v_fmac_f32_e32 v43, v155, v16
	v_fmac_f32_e32 v27, v156, v16
	v_fmac_f32_e32 v26, v157, v16
	v_fmac_f32_e32 v25, v158, v16
	v_fmac_f32_e32 v23, v144, v16
	v_fmac_f32_e32 v24, v146, v16
	v_fmac_f32_e32 v22, v61, v16
	v_fmac_f32_e32 v21, v145, v16
	v_fmac_f32_e32 v20, v147, v16
	v_fmac_f32_e32 v19, v148, v16
	v_fmac_f32_e32 v18, v149, v16
	v_fma_f32 v17, v150, v16, v60
	s_waitcnt lgkmcnt(0)
	v_lshlrev_b32_e32 v16, 16, v101
	ds_read_u16 v98, v89 offset:16384
	ds_read_u16 v99, v89 offset:17408
	ds_read_u16 v100, v89 offset:18432
	ds_read_u16 v101, v89 offset:19456
	ds_read_u16 v102, v89 offset:20480
	ds_read_u16 v103, v89 offset:21504
	ds_read_u16 v104, v89 offset:22528
	ds_read_u16 v105, v89 offset:23552
	v_fmac_f32_e32 v49, v152, v16
	v_fmac_f32_e32 v47, v154, v16
	v_fmac_f32_e32 v45, v151, v16
	v_fmac_f32_e32 v43, v153, v16
	v_fmac_f32_e32 v27, v155, v16
	v_fmac_f32_e32 v26, v156, v16
	v_fmac_f32_e32 v25, v157, v16
	v_fmac_f32_e32 v23, v158, v16
	v_fmac_f32_e32 v24, v144, v16
	v_fmac_f32_e32 v22, v146, v16
	v_fmac_f32_e32 v21, v61, v16
	v_fmac_f32_e32 v20, v145, v16
	v_fmac_f32_e32 v19, v147, v16
	v_fmac_f32_e32 v18, v148, v16
	v_fmac_f32_e32 v17, v149, v16
	v_fma_f32 v16, v150, v16, v60
	s_waitcnt lgkmcnt(7)
	v_lshlrev_b32_e32 v98, 16, v98
	v_fmac_f32_e32 v49, v161, v98
	v_fmac_f32_e32 v47, v152, v98
	v_fmac_f32_e32 v45, v154, v98
	v_fmac_f32_e32 v43, v151, v98
	v_fmac_f32_e32 v27, v153, v98
	v_fmac_f32_e32 v26, v155, v98
	v_fmac_f32_e32 v25, v156, v98
	v_fmac_f32_e32 v23, v157, v98
	v_fmac_f32_e32 v24, v158, v98
	v_fmac_f32_e32 v22, v144, v98
	v_fmac_f32_e32 v21, v146, v98
	v_fmac_f32_e32 v20, v61, v98
	v_fmac_f32_e32 v19, v145, v98
	v_fmac_f32_e32 v18, v147, v98
	v_fmac_f32_e32 v17, v148, v98
	v_fmac_f32_e32 v16, v149, v98
	s_waitcnt lgkmcnt(6)
	v_lshlrev_b32_e32 v98, 16, v99
	v_fmac_f32_e32 v49, v160, v98
	v_fmac_f32_e32 v47, v161, v98
	v_fmac_f32_e32 v45, v152, v98
	v_fmac_f32_e32 v43, v154, v98
	v_fmac_f32_e32 v27, v151, v98
	v_fmac_f32_e32 v26, v153, v98
	v_fmac_f32_e32 v25, v155, v98
	v_fmac_f32_e32 v23, v156, v98
	v_fmac_f32_e32 v24, v157, v98
	v_fmac_f32_e32 v22, v158, v98
	v_fmac_f32_e32 v21, v144, v98
	v_fmac_f32_e32 v20, v146, v98
	v_fmac_f32_e32 v19, v61, v98
	v_fmac_f32_e32 v18, v145, v98
	v_fmac_f32_e32 v17, v147, v98
	v_fmac_f32_e32 v16, v148, v98
	s_waitcnt lgkmcnt(5)
	v_lshlrev_b32_e32 v98, 16, v100
	v_fmac_f32_e32 v49, v159, v98
	v_fmac_f32_e32 v47, v160, v98
	v_fmac_f32_e32 v45, v161, v98
	v_fmac_f32_e32 v43, v152, v98
	v_fmac_f32_e32 v27, v154, v98
	v_fmac_f32_e32 v26, v151, v98
	v_fmac_f32_e32 v25, v153, v98
	v_fmac_f32_e32 v23, v155, v98
	v_fmac_f32_e32 v24, v156, v98
	v_fmac_f32_e32 v22, v157, v98
	v_fmac_f32_e32 v21, v158, v98
	v_fmac_f32_e32 v20, v144, v98
	v_fmac_f32_e32 v19, v146, v98
	v_fmac_f32_e32 v18, v61, v98
	v_fmac_f32_e32 v17, v145, v98
	v_fmac_f32_e32 v16, v147, v98
	s_waitcnt lgkmcnt(4)
	v_lshlrev_b32_e32 v98, 16, v101
	v_fmac_f32_e32 v49, v68, v98
	v_fmac_f32_e32 v47, v159, v98
	v_fmac_f32_e32 v45, v160, v98
	v_fmac_f32_e32 v43, v161, v98
	v_fmac_f32_e32 v27, v152, v98
	v_fmac_f32_e32 v26, v154, v98
	v_fmac_f32_e32 v25, v151, v98
	v_fmac_f32_e32 v23, v153, v98
	v_fmac_f32_e32 v24, v155, v98
	v_fmac_f32_e32 v22, v156, v98
	v_fmac_f32_e32 v21, v157, v98
	v_fmac_f32_e32 v20, v158, v98
	v_fmac_f32_e32 v19, v144, v98
	v_fmac_f32_e32 v18, v146, v98
	v_fmac_f32_e32 v17, v61, v98
	v_fmac_f32_e32 v16, v145, v98
	s_waitcnt lgkmcnt(3)
	v_lshlrev_b32_e32 v98, 16, v102
	v_fmac_f32_e32 v49, v69, v98
	v_fmac_f32_e32 v47, v68, v98
	v_fmac_f32_e32 v45, v159, v98
	v_fmac_f32_e32 v43, v160, v98
	v_fmac_f32_e32 v27, v161, v98
	v_fmac_f32_e32 v26, v152, v98
	v_fmac_f32_e32 v25, v154, v98
	v_fmac_f32_e32 v23, v151, v98
	v_fmac_f32_e32 v24, v153, v98
	v_fmac_f32_e32 v22, v155, v98
	v_fmac_f32_e32 v21, v156, v98
	v_fmac_f32_e32 v20, v157, v98
	v_fmac_f32_e32 v19, v158, v98
	v_fmac_f32_e32 v18, v144, v98
	v_fmac_f32_e32 v17, v146, v98
	v_fmac_f32_e32 v16, v61, v98
	s_waitcnt lgkmcnt(2)
	v_lshlrev_b32_e32 v98, 16, v103
	v_fmac_f32_e32 v49, v62, v98
	v_fmac_f32_e32 v47, v69, v98
	v_fmac_f32_e32 v45, v68, v98
	v_fmac_f32_e32 v43, v159, v98
	v_fmac_f32_e32 v27, v160, v98
	v_fmac_f32_e32 v26, v161, v98
	v_fmac_f32_e32 v25, v152, v98
	v_fmac_f32_e32 v23, v154, v98
	v_fmac_f32_e32 v24, v151, v98
	v_fmac_f32_e32 v22, v153, v98
	v_fmac_f32_e32 v21, v155, v98
	v_fmac_f32_e32 v20, v156, v98
	v_fmac_f32_e32 v19, v157, v98
	v_fmac_f32_e32 v18, v158, v98
	v_fmac_f32_e32 v17, v144, v98
	v_fmac_f32_e32 v16, v146, v98
	s_waitcnt lgkmcnt(1)
	v_lshlrev_b32_e32 v98, 16, v104
	v_fmac_f32_e32 v49, v63, v98
	v_fmac_f32_e32 v47, v62, v98
	v_fmac_f32_e32 v45, v69, v98
	v_fmac_f32_e32 v43, v68, v98
	v_fmac_f32_e32 v27, v159, v98
	v_fmac_f32_e32 v26, v160, v98
	v_fmac_f32_e32 v25, v161, v98
	v_fmac_f32_e32 v23, v152, v98
	v_fmac_f32_e32 v24, v154, v98
	v_fmac_f32_e32 v22, v151, v98
	v_fmac_f32_e32 v21, v153, v98
	v_fmac_f32_e32 v20, v155, v98
	v_fmac_f32_e32 v19, v156, v98
	v_fmac_f32_e32 v18, v157, v98
	v_fmac_f32_e32 v17, v158, v98
	v_fmac_f32_e32 v16, v144, v98
	s_waitcnt lgkmcnt(0)
	v_lshlrev_b32_e32 v98, 16, v105
	v_fmac_f32_e32 v49, v66, v98
	v_fmac_f32_e32 v47, v63, v98
	v_fmac_f32_e32 v45, v62, v98
	v_fmac_f32_e32 v43, v69, v98
	v_fmac_f32_e32 v27, v68, v98
	v_fmac_f32_e32 v26, v159, v98
	v_fmac_f32_e32 v25, v160, v98
	v_fmac_f32_e32 v23, v161, v98
	v_fmac_f32_e32 v24, v152, v98
	v_fmac_f32_e32 v22, v154, v98
	v_fmac_f32_e32 v21, v151, v98
	v_fmac_f32_e32 v20, v153, v98
	v_fmac_f32_e32 v19, v155, v98
	v_fmac_f32_e32 v18, v156, v98
	v_fmac_f32_e32 v17, v157, v98
	v_fmac_f32_e32 v16, v158, v98
	ds_read_u16 v98, v89 offset:24576
	ds_read_u16 v99, v89 offset:25600
	ds_read_u16 v100, v89 offset:26624
	ds_read_u16 v101, v89 offset:27648
	ds_read_u16 v102, v89 offset:28672
	ds_read_u16 v103, v89 offset:29696
	ds_read_u16 v104, v89 offset:30720
	ds_read_u16 v105, v89 offset:31744
	s_waitcnt lgkmcnt(7)
	v_lshlrev_b32_e32 v98, 16, v98
	v_fmac_f32_e32 v49, v67, v98
	v_fmac_f32_e32 v47, v66, v98
	v_fmac_f32_e32 v45, v63, v98
	v_fmac_f32_e32 v43, v62, v98
	v_fmac_f32_e32 v27, v69, v98
	v_fmac_f32_e32 v26, v68, v98
	v_fmac_f32_e32 v25, v159, v98
	v_fmac_f32_e32 v23, v160, v98
	v_fmac_f32_e32 v24, v161, v98
	v_fmac_f32_e32 v22, v152, v98
	v_fmac_f32_e32 v21, v154, v98
	v_fmac_f32_e32 v20, v151, v98
	v_fmac_f32_e32 v19, v153, v98
	v_fmac_f32_e32 v18, v155, v98
	v_fmac_f32_e32 v17, v156, v98
	v_fmac_f32_e32 v16, v157, v98
	s_waitcnt lgkmcnt(6)
	v_lshlrev_b32_e32 v98, 16, v99
	v_fmac_f32_e32 v49, v74, v98
	v_fmac_f32_e32 v47, v67, v98
	v_fmac_f32_e32 v45, v66, v98
	v_fmac_f32_e32 v43, v63, v98
	v_fmac_f32_e32 v27, v62, v98
	v_fmac_f32_e32 v26, v69, v98
	v_fmac_f32_e32 v25, v68, v98
	v_fmac_f32_e32 v23, v159, v98
	v_fmac_f32_e32 v24, v160, v98
	v_fmac_f32_e32 v22, v161, v98
	v_fmac_f32_e32 v21, v152, v98
	v_fmac_f32_e32 v20, v154, v98
	v_fmac_f32_e32 v19, v151, v98
	v_fmac_f32_e32 v18, v153, v98
	v_fmac_f32_e32 v17, v155, v98
	v_fmac_f32_e32 v16, v156, v98
	s_waitcnt lgkmcnt(5)
	v_lshlrev_b32_e32 v98, 16, v100
	v_fmac_f32_e32 v49, v75, v98
	v_fmac_f32_e32 v47, v74, v98
	v_fmac_f32_e32 v45, v67, v98
	v_fmac_f32_e32 v43, v66, v98
	v_fmac_f32_e32 v27, v63, v98
	v_fmac_f32_e32 v26, v62, v98
	v_fmac_f32_e32 v25, v69, v98
	v_fmac_f32_e32 v23, v68, v98
	v_fmac_f32_e32 v24, v159, v98
	v_fmac_f32_e32 v22, v160, v98
	v_fmac_f32_e32 v21, v161, v98
	v_fmac_f32_e32 v20, v152, v98
	v_fmac_f32_e32 v19, v154, v98
	v_fmac_f32_e32 v18, v151, v98
	v_fmac_f32_e32 v17, v153, v98
	v_fmac_f32_e32 v16, v155, v98
	s_waitcnt lgkmcnt(4)
	v_lshlrev_b32_e32 v98, 16, v101
	v_fmac_f32_e32 v49, v72, v98
	v_fmac_f32_e32 v47, v75, v98
	v_fmac_f32_e32 v45, v74, v98
	v_fmac_f32_e32 v43, v67, v98
	v_fmac_f32_e32 v27, v66, v98
	v_fmac_f32_e32 v26, v63, v98
	v_fmac_f32_e32 v25, v62, v98
	v_fmac_f32_e32 v23, v69, v98
	v_fmac_f32_e32 v24, v68, v98
	v_fmac_f32_e32 v22, v159, v98
	v_fmac_f32_e32 v21, v160, v98
	v_fmac_f32_e32 v20, v161, v98
	v_fmac_f32_e32 v19, v152, v98
	v_fmac_f32_e32 v18, v154, v98
	v_fmac_f32_e32 v17, v151, v98
	v_fmac_f32_e32 v16, v153, v98
	s_waitcnt lgkmcnt(3)
	v_lshlrev_b32_e32 v98, 16, v102
	v_fmac_f32_e32 v49, v73, v98
	v_fmac_f32_e32 v47, v72, v98
	v_fmac_f32_e32 v45, v75, v98
	v_fmac_f32_e32 v43, v74, v98
	v_fmac_f32_e32 v27, v67, v98
	v_fmac_f32_e32 v26, v66, v98
	v_fmac_f32_e32 v25, v63, v98
	v_fmac_f32_e32 v23, v62, v98
	v_fmac_f32_e32 v24, v69, v98
	v_fmac_f32_e32 v22, v68, v98
	v_fmac_f32_e32 v21, v159, v98
	v_fmac_f32_e32 v20, v160, v98
	v_fmac_f32_e32 v19, v161, v98
	v_fmac_f32_e32 v18, v152, v98
	v_fmac_f32_e32 v17, v154, v98
	v_fmac_f32_e32 v16, v151, v98
	s_waitcnt lgkmcnt(2)
	v_lshlrev_b32_e32 v98, 16, v103
	v_fmac_f32_e32 v49, v70, v98
	v_fmac_f32_e32 v47, v73, v98
	v_fmac_f32_e32 v45, v72, v98
	v_fmac_f32_e32 v43, v75, v98
	v_fmac_f32_e32 v27, v74, v98
	v_fmac_f32_e32 v26, v67, v98
	v_fmac_f32_e32 v25, v66, v98
	v_fmac_f32_e32 v23, v63, v98
	v_fmac_f32_e32 v24, v62, v98
	v_fmac_f32_e32 v22, v69, v98
	v_fmac_f32_e32 v21, v68, v98
	v_fmac_f32_e32 v20, v159, v98
	v_fmac_f32_e32 v19, v160, v98
	v_fmac_f32_e32 v18, v161, v98
	v_fmac_f32_e32 v17, v152, v98
	v_fmac_f32_e32 v16, v154, v98
	s_waitcnt lgkmcnt(1)
	v_lshlrev_b32_e32 v98, 16, v104
	v_fmac_f32_e32 v49, v71, v98
	v_fmac_f32_e32 v47, v70, v98
	v_fmac_f32_e32 v45, v73, v98
	v_fmac_f32_e32 v43, v72, v98
	v_fmac_f32_e32 v27, v75, v98
	v_fmac_f32_e32 v26, v74, v98
	v_fmac_f32_e32 v25, v67, v98
	v_fmac_f32_e32 v23, v66, v98
	v_fmac_f32_e32 v24, v63, v98
	v_fmac_f32_e32 v22, v62, v98
	v_fmac_f32_e32 v21, v69, v98
	v_fmac_f32_e32 v20, v68, v98
	v_fmac_f32_e32 v19, v159, v98
	v_fmac_f32_e32 v18, v160, v98
	v_fmac_f32_e32 v17, v161, v98
	v_fmac_f32_e32 v16, v152, v98
	s_waitcnt lgkmcnt(0)
	v_lshlrev_b32_e32 v98, 16, v105
	v_fmac_f32_e32 v47, v71, v98
	v_fmac_f32_e32 v45, v70, v98
	v_fmac_f32_e32 v43, v73, v98
	v_fmac_f32_e32 v27, v72, v98
	v_fmac_f32_e32 v26, v75, v98
	v_fmac_f32_e32 v25, v74, v98
	v_fmac_f32_e32 v23, v67, v98
	v_fmac_f32_e32 v24, v66, v98
	v_fmac_f32_e32 v22, v63, v98
	v_fmac_f32_e32 v21, v62, v98
	v_fmac_f32_e32 v20, v69, v98
	v_fmac_f32_e32 v19, v68, v98
	v_fmac_f32_e32 v18, v159, v98
	v_fmac_f32_e32 v17, v160, v98
	v_fmac_f32_e32 v16, v161, v98
	ds_read_u16 v104, v86 offset:31744
	ds_read_u16 v105, v87 offset:15360
	ds_read_u16 v98, v89 offset:32768
	ds_read_u16 v99, v89 offset:33792
	ds_read_u16 v100, v89 offset:34816
	ds_read_u16 v101, v89 offset:35840
	ds_read_u16 v102, v89 offset:36864
	ds_read_u16 v103, v89 offset:37888
	s_waitcnt lgkmcnt(5)
	v_lshlrev_b32_e32 v98, 16, v98
	v_fmac_f32_e32 v45, v71, v98
	v_fmac_f32_e32 v43, v70, v98
	v_fmac_f32_e32 v27, v73, v98
	v_fmac_f32_e32 v26, v72, v98
	v_fmac_f32_e32 v25, v75, v98
	v_fmac_f32_e32 v23, v74, v98
	v_fmac_f32_e32 v24, v67, v98
	v_fmac_f32_e32 v22, v66, v98
	v_fmac_f32_e32 v21, v63, v98
	v_fmac_f32_e32 v20, v62, v98
	v_fmac_f32_e32 v19, v69, v98
	v_fmac_f32_e32 v18, v68, v98
	v_fmac_f32_e32 v17, v159, v98
	v_fmac_f32_e32 v16, v160, v98
	s_waitcnt lgkmcnt(4)
	v_lshlrev_b32_e32 v98, 16, v99
	v_fmac_f32_e32 v43, v71, v98
	v_fmac_f32_e32 v27, v70, v98
	v_fmac_f32_e32 v26, v73, v98
	v_fmac_f32_e32 v25, v72, v98
	v_fmac_f32_e32 v23, v75, v98
	v_fmac_f32_e32 v24, v74, v98
	v_fmac_f32_e32 v22, v67, v98
	v_fmac_f32_e32 v21, v66, v98
	v_fmac_f32_e32 v20, v63, v98
	v_fmac_f32_e32 v19, v62, v98
	v_fmac_f32_e32 v18, v69, v98
	v_fmac_f32_e32 v17, v68, v98
	v_fmac_f32_e32 v16, v159, v98
	s_waitcnt lgkmcnt(3)
	v_lshlrev_b32_e32 v98, 16, v100
	v_fmac_f32_e32 v27, v71, v98
	v_fmac_f32_e32 v26, v70, v98
	v_fmac_f32_e32 v25, v73, v98
	v_fmac_f32_e32 v23, v72, v98
	v_fmac_f32_e32 v24, v75, v98
	v_fmac_f32_e32 v22, v74, v98
	v_fmac_f32_e32 v21, v67, v98
	v_fmac_f32_e32 v20, v66, v98
	v_fmac_f32_e32 v19, v63, v98
	v_fmac_f32_e32 v18, v62, v98
	v_fmac_f32_e32 v17, v69, v98
	v_fmac_f32_e32 v16, v68, v98
	s_waitcnt lgkmcnt(2)
	v_lshlrev_b32_e32 v98, 16, v101
	v_fmac_f32_e32 v26, v71, v98
	v_fmac_f32_e32 v25, v70, v98
	v_fmac_f32_e32 v23, v73, v98
	v_fmac_f32_e32 v24, v72, v98
	v_fmac_f32_e32 v22, v75, v98
	v_fmac_f32_e32 v21, v74, v98
	v_fmac_f32_e32 v20, v67, v98
	v_fmac_f32_e32 v19, v66, v98
	v_fmac_f32_e32 v18, v63, v98
	v_fmac_f32_e32 v17, v62, v98
	v_fmac_f32_e32 v16, v69, v98
	s_waitcnt lgkmcnt(1)
	v_lshlrev_b32_e32 v98, 16, v102
	v_fmac_f32_e32 v25, v71, v98
	v_fmac_f32_e32 v23, v70, v98
	v_fmac_f32_e32 v24, v73, v98
	v_fmac_f32_e32 v22, v72, v98
	v_fmac_f32_e32 v21, v75, v98
	v_fmac_f32_e32 v20, v74, v98
	v_fmac_f32_e32 v19, v67, v98
	v_fmac_f32_e32 v18, v66, v98
	v_fmac_f32_e32 v17, v63, v98
	v_fmac_f32_e32 v16, v62, v98
	s_waitcnt lgkmcnt(0)
	v_lshlrev_b32_e32 v98, 16, v103
	v_fmac_f32_e32 v23, v71, v98
	v_fmac_f32_e32 v24, v70, v98
	v_fmac_f32_e32 v22, v73, v98
	v_fmac_f32_e32 v21, v72, v98
	v_fmac_f32_e32 v20, v75, v98
	v_fmac_f32_e32 v19, v74, v98
	v_fmac_f32_e32 v18, v67, v98
	v_fmac_f32_e32 v17, v66, v98
	v_fmac_f32_e32 v16, v63, v98
	ds_read_u16 v98, v89 offset:38912
	ds_read_u16 v99, v89 offset:39936
	ds_read_u16 v100, v89 offset:40960
	ds_read_u16 v101, v89 offset:41984
	ds_read_u16 v102, v89 offset:43008
	ds_read_u16 v103, v89 offset:44032
	ds_read_u16 v106, v89 offset:45056
	ds_read_u16 v107, v89 offset:46080
	s_waitcnt lgkmcnt(7)
	v_lshlrev_b32_e32 v98, 16, v98
	v_fmac_f32_e32 v24, v71, v98
	v_fmac_f32_e32 v22, v70, v98
	v_fmac_f32_e32 v21, v73, v98
	v_fmac_f32_e32 v20, v72, v98
	v_fmac_f32_e32 v19, v75, v98
	v_fmac_f32_e32 v18, v74, v98
	v_fmac_f32_e32 v17, v67, v98
	v_fmac_f32_e32 v16, v66, v98
	s_waitcnt lgkmcnt(6)
	v_lshlrev_b32_e32 v98, 16, v99
	v_fmac_f32_e32 v22, v71, v98
	v_fmac_f32_e32 v21, v70, v98
	v_fmac_f32_e32 v20, v73, v98
	v_fmac_f32_e32 v19, v72, v98
	v_fmac_f32_e32 v18, v75, v98
	v_fmac_f32_e32 v17, v74, v98
	v_fmac_f32_e32 v16, v67, v98
	s_waitcnt lgkmcnt(5)
	v_lshlrev_b32_e32 v98, 16, v100
	v_fmac_f32_e32 v21, v71, v98
	v_fmac_f32_e32 v20, v70, v98
	v_fmac_f32_e32 v19, v73, v98
	v_fmac_f32_e32 v18, v72, v98
	v_fmac_f32_e32 v17, v75, v98
	v_fmac_f32_e32 v16, v74, v98
	s_waitcnt lgkmcnt(4)
	v_lshlrev_b32_e32 v98, 16, v101
	v_fmac_f32_e32 v20, v71, v98
	v_fmac_f32_e32 v19, v70, v98
	v_fmac_f32_e32 v18, v73, v98
	v_fmac_f32_e32 v17, v72, v98
	v_fmac_f32_e32 v16, v75, v98
	s_waitcnt lgkmcnt(3)
	v_lshlrev_b32_e32 v98, 16, v102
	v_fmac_f32_e32 v19, v71, v98
	v_fmac_f32_e32 v18, v70, v98
	v_fmac_f32_e32 v17, v73, v98
	v_fmac_f32_e32 v16, v72, v98
	s_waitcnt lgkmcnt(2)
	v_lshlrev_b32_e32 v98, 16, v103
	v_fmac_f32_e32 v18, v71, v98
	v_fmac_f32_e32 v17, v70, v98
	v_fmac_f32_e32 v16, v73, v98
	s_waitcnt lgkmcnt(1)
	v_lshlrev_b32_e32 v98, 16, v106
	v_fmac_f32_e32 v17, v71, v98
	v_fmac_f32_e32 v16, v70, v98
	s_waitcnt lgkmcnt(0)
	v_lshlrev_b32_e32 v98, 16, v107
	v_cmp_lt_i32_e32 vcc, v224, v218
	v_fmac_f32_e32 v16, v71, v98
	v_cndmask_b32_e64 v114, v49, v24, s[26:27]
	v_cndmask_b32_e32 v98, v217, v224, vcc
	v_lshlrev_b32_e32 v98, 2, v98
	ds_bpermute_b32 v114, v98, v114
	v_mul_f32_e32 v99, v49, v49
	v_mul_f32_e32 v109, v24, v24
	v_cndmask_b32_e64 v118, v24, v49, s[26:27]
	v_mul_f32_e32 v100, v47, v47
	s_waitcnt lgkmcnt(0)
	v_add_f32_e32 v114, v118, v114
	v_cndmask_b32_e64 v118, v99, v109, s[26:27]
	v_mul_f32_e32 v110, v22, v22
	v_cndmask_b32_e64 v99, v109, v99, s[26:27]
	ds_bpermute_b32 v109, v98, v118
	v_cndmask_b32_e64 v118, v47, v22, s[26:27]
	ds_bpermute_b32 v118, v98, v118
	v_cndmask_b32_e64 v119, v100, v110, s[26:27]
	ds_bpermute_b32 v119, v98, v119
	s_waitcnt lgkmcnt(2)
	v_add_f32_e32 v109, v99, v109
	v_cndmask_b32_e64 v99, v22, v47, s[26:27]
	s_waitcnt lgkmcnt(1)
	v_add_f32_e32 v118, v99, v118
	v_cndmask_b32_e64 v99, v110, v100, s[26:27]
	v_mul_f32_e32 v101, v45, v45
	v_mul_f32_e32 v111, v21, v21
	s_waitcnt lgkmcnt(0)
	v_add_f32_e32 v100, v99, v119
	v_cndmask_b32_e64 v99, v45, v21, s[26:27]
	ds_bpermute_b32 v99, v98, v99
	v_cndmask_b32_e64 v119, v101, v111, s[26:27]
	ds_bpermute_b32 v119, v98, v119
	v_cndmask_b32_e64 v120, v43, v20, s[26:27]
	ds_bpermute_b32 v120, v98, v120
	v_cndmask_b32_e64 v110, v21, v45, s[26:27]
	s_waitcnt lgkmcnt(2)
	v_add_f32_e32 v110, v110, v99
	v_cndmask_b32_e64 v99, v111, v101, s[26:27]
	v_mul_f32_e32 v102, v43, v43
	v_mul_f32_e32 v112, v20, v20
	s_waitcnt lgkmcnt(1)
	v_add_f32_e32 v101, v99, v119
	v_cndmask_b32_e64 v99, v20, v43, s[26:27]
	s_waitcnt lgkmcnt(0)
	v_add_f32_e32 v111, v99, v120
	v_cndmask_b32_e64 v99, v102, v112, s[26:27]
	v_mul_f32_e32 v103, v27, v27
	v_mul_f32_e32 v113, v19, v19
	v_cndmask_b32_e64 v102, v112, v102, s[26:27]
	ds_bpermute_b32 v99, v98, v99
	v_cndmask_b32_e64 v112, v27, v19, s[26:27]
	ds_bpermute_b32 v112, v98, v112
	v_cndmask_b32_e64 v119, v103, v113, s[26:27]
	ds_bpermute_b32 v119, v98, v119
	s_waitcnt lgkmcnt(2)
	v_add_f32_e32 v102, v102, v99
	v_cndmask_b32_e64 v99, v19, v27, s[26:27]
	s_waitcnt lgkmcnt(1)
	v_add_f32_e32 v112, v99, v112
	v_cndmask_b32_e64 v99, v113, v103, s[26:27]
	v_mul_f32_e32 v106, v26, v26
	v_mul_f32_e32 v115, v18, v18
	s_waitcnt lgkmcnt(0)
	v_add_f32_e32 v103, v99, v119
	v_cndmask_b32_e64 v99, v26, v18, s[26:27]
	ds_bpermute_b32 v99, v98, v99
	v_cndmask_b32_e64 v119, v106, v115, s[26:27]
	ds_bpermute_b32 v119, v98, v119
	v_cndmask_b32_e64 v120, v25, v17, s[26:27]
	ds_bpermute_b32 v120, v98, v120
	v_cndmask_b32_e64 v113, v18, v26, s[26:27]
	s_waitcnt lgkmcnt(2)
	v_add_f32_e32 v113, v113, v99
	v_cndmask_b32_e64 v99, v115, v106, s[26:27]
	v_mul_f32_e32 v107, v25, v25
	v_mul_f32_e32 v116, v17, v17
	s_waitcnt lgkmcnt(1)
	v_add_f32_e32 v106, v99, v119
	v_cndmask_b32_e64 v99, v17, v25, s[26:27]
	s_waitcnt lgkmcnt(0)
	v_add_f32_e32 v115, v99, v120
	v_cndmask_b32_e64 v99, v107, v116, s[26:27]
	v_mul_f32_e32 v108, v23, v23
	v_mul_f32_e32 v117, v16, v16
	v_cndmask_b32_e64 v107, v116, v107, s[26:27]
	ds_bpermute_b32 v99, v98, v99
	v_cndmask_b32_e64 v116, v23, v16, s[26:27]
	ds_bpermute_b32 v116, v98, v116
	v_cndmask_b32_e64 v119, v108, v117, s[26:27]
	ds_bpermute_b32 v119, v98, v119
	s_waitcnt lgkmcnt(2)
	v_add_f32_e32 v107, v107, v99
	v_cndmask_b32_e64 v99, v16, v23, s[26:27]
	s_waitcnt lgkmcnt(1)
	v_add_f32_e32 v116, v99, v116
	v_cndmask_b32_e64 v99, v117, v108, s[26:27]
	v_cmp_lt_i32_e32 vcc, v223, v218
	s_waitcnt lgkmcnt(0)
	v_add_f32_e32 v108, v99, v119
	v_cndmask_b32_e64 v117, v114, v112, s[4:5]
	v_cndmask_b32_e32 v99, v217, v223, vcc
	v_lshlrev_b32_e32 v99, 2, v99
	v_cndmask_b32_e64 v112, v112, v114, s[4:5]
	ds_bpermute_b32 v114, v99, v117
	v_cndmask_b32_e64 v117, v109, v103, s[4:5]
	v_cndmask_b32_e64 v119, v118, v113, s[4:5]
	v_cndmask_b32_e64 v103, v103, v109, s[4:5]
	v_cndmask_b32_e64 v109, v113, v118, s[4:5]
	v_cndmask_b32_e64 v113, v100, v106, s[4:5]
	v_cndmask_b32_e64 v100, v106, v100, s[4:5]
	ds_bpermute_b32 v106, v99, v113
	v_cndmask_b32_e64 v113, v110, v115, s[4:5]
	s_waitcnt lgkmcnt(1)
	v_add_f32_e32 v112, v112, v114
	ds_bpermute_b32 v113, v99, v113
	v_cndmask_b32_e64 v114, v101, v107, s[4:5]
	ds_bpermute_b32 v114, v99, v114
	s_waitcnt lgkmcnt(2)
	v_add_f32_e32 v106, v100, v106
	v_cndmask_b32_e64 v100, v115, v110, s[4:5]
	s_waitcnt lgkmcnt(1)
	v_add_f32_e32 v110, v100, v113
	v_cndmask_b32_e64 v100, v107, v101, s[4:5]
	ds_bpermute_b32 v117, v99, v117
	s_waitcnt lgkmcnt(1)
	v_add_f32_e32 v101, v100, v114
	v_cndmask_b32_e64 v100, v111, v116, s[4:5]
	ds_bpermute_b32 v119, v99, v119
	v_cndmask_b32_e64 v107, v116, v111, s[4:5]
	ds_bpermute_b32 v111, v99, v100
	v_cndmask_b32_e64 v100, v102, v108, s[4:5]
	ds_bpermute_b32 v113, v99, v100
	v_cmp_lt_i32_e32 vcc, v222, v218
	s_waitcnt lgkmcnt(3)
	v_add_f32_e32 v103, v103, v117
	s_waitcnt lgkmcnt(2)
	v_add_f32_e32 v109, v109, v119
	v_cndmask_b32_e32 v100, v217, v222, vcc
	v_lshlrev_b32_e32 v100, 2, v100
	v_cndmask_b32_e64 v114, v112, v110, s[6:7]
	s_waitcnt lgkmcnt(1)
	v_add_f32_e32 v107, v107, v111
	v_cndmask_b32_e64 v102, v108, v102, s[4:5]
	v_cndmask_b32_e64 v108, v110, v112, s[6:7]
	v_cndmask_b32_e64 v110, v103, v101, s[6:7]
	s_waitcnt lgkmcnt(0)
	v_add_f32_e32 v102, v102, v113
	v_cndmask_b32_e64 v101, v101, v103, s[6:7]
	ds_bpermute_b32 v103, v100, v110
	v_cndmask_b32_e64 v110, v109, v107, s[6:7]
	ds_bpermute_b32 v110, v100, v110
	v_cndmask_b32_e64 v111, v106, v102, s[6:7]
	ds_bpermute_b32 v114, v100, v114
	ds_bpermute_b32 v111, v100, v111
	s_waitcnt lgkmcnt(3)
	v_add_f32_e32 v103, v101, v103
	v_cndmask_b32_e64 v101, v107, v109, s[6:7]
	s_waitcnt lgkmcnt(2)
	v_add_f32_e32 v107, v101, v110
	v_cndmask_b32_e64 v101, v102, v106, s[6:7]
	v_cmp_lt_i32_e32 vcc, v221, v218
	s_waitcnt lgkmcnt(1)
	v_add_f32_e32 v108, v108, v114
	s_waitcnt lgkmcnt(0)
	v_add_f32_e32 v102, v101, v111
	v_cndmask_b32_e32 v101, v217, v221, vcc
	v_lshlrev_b32_e32 v101, 2, v101
	v_cndmask_b32_e64 v106, v108, v107, s[8:9]
	v_cndmask_b32_e64 v109, v103, v102, s[8:9]
	ds_bpermute_b32 v106, v101, v106
	ds_bpermute_b32 v109, v101, v109
	v_cndmask_b32_e64 v107, v107, v108, s[8:9]
	v_cndmask_b32_e64 v102, v102, v103, s[8:9]
	v_cmp_lt_i32_e32 vcc, v220, v218
	s_waitcnt lgkmcnt(1)
	v_add_f32_e32 v122, v107, v106
	s_waitcnt lgkmcnt(0)
	v_add_f32_e32 v103, v102, v109
	v_cndmask_b32_e32 v102, v217, v220, vcc
	v_lshlrev_b32_e32 v102, 2, v102
	v_cndmask_b32_e64 v106, v122, v103, s[10:11]
	ds_bpermute_b32 v123, v102, v106
	ds_read_u16 v113, v86 offset:57344
	ds_read_u16 v114, v86 offset:58368
	ds_read_u16 v115, v86 offset:59392
	ds_read_u16 v116, v86 offset:60416
	ds_read_u16 v117, v86 offset:61440
	ds_read_u16 v118, v86 offset:62464
	ds_read_u16 v119, v86 offset:63488
	ds_read_u16 v120, v86 offset:64512
	ds_read_u16 v106, v86 offset:50176
	ds_read_u16 v107, v86 offset:51200
	ds_read_u16 v108, v86 offset:52224
	ds_read_u16 v109, v86 offset:53248
	ds_read_u16 v110, v86 offset:54272
	ds_read_u16 v111, v86 offset:55296
	ds_read_u16 v112, v86 offset:56320
	ds_read_u16 v121, v86 offset:49152
	v_cndmask_b32_e64 v103, v103, v122, s[10:11]
	v_cmp_lt_i32_e32 vcc, v219, v218
	s_waitcnt lgkmcnt(14)
	v_add_f32_e32 v122, v103, v123
	v_cndmask_b32_e32 v103, v217, v219, vcc
	v_lshlrev_b32_e32 v103, 2, v103
	ds_bpermute_b32 v123, v103, v122
	s_and_saveexec_b64 s[14:15], s[12:13]
	s_cbranch_execz .LBB0_433
	s_waitcnt lgkmcnt(0)
	v_add_f32_e32 v122, v122, v123
	ds_write_b32 v91, v122
	s_branch .LBB0_433
.LBB0_564:
	s_and_b64 vcc, exec, s[18:19]
	s_cbranch_vccz .LBB0_566
	ds_read_u16 v0, v86 offset:14336
	ds_read_u16 v1, v86 offset:15360
	ds_read_u16 v2, v86 offset:16384
	ds_read_u16 v4, v86 offset:18432
	ds_read_u16 v14, v86 offset:19456
	ds_read_u16 v5, v86 offset:17408
	ds_read_u16 v6, v86 offset:12288
	ds_read_u16 v7, v86 offset:13312
	s_waitcnt lgkmcnt(0)
	v_lshlrev_b32_e32 v1, 16, v1
	v_lshlrev_b32_e32 v3, 16, v2
	v_mov_b32_e32 v2, v1
	v_lshlrev_b32_e32 v0, 16, v0
	v_lshlrev_b32_e32 v13, 16, v5
	v_lshlrev_b32_e32 v17, 16, v4
	v_lshlrev_b32_e32 v5, 16, v7
	v_lshlrev_b32_e32 v4, 16, v6
	v_pk_add_f32 v[8:9], v[2:3], 0 op_sel_hi:[1,0]
	v_pk_mov_b32 v[10:11], v[4:5], v[0:1] op_sel:[1,0]
	v_pk_add_f32 v[8:9], v[8:9], v[0:1]
	v_mov_b32_e32 v16, v13
	v_pk_add_f32 v[8:9], v[8:9], v[10:11]
	v_mov_b32_e32 v12, v3
	v_pk_add_f32 v[4:5], v[8:9], v[4:5]
	v_pk_add_f32 v[8:9], v[16:17], 0 op_sel_hi:[1,0]
	v_lshlrev_b32_e32 v10, 16, v14
	v_pk_add_f32 v[8:9], v[8:9], v[12:13]
	s_cmp_eq_u32 s55, 0
	v_pk_add_f32 v[8:9], v[8:9], v[2:3]
	s_cselect_b64 vcc, -1, 0
	v_pk_add_f32 v[8:9], v[8:9], v[0:1]
	ds_read_u16 v0, v86 offset:20480
	ds_read_u16 v2, v86 offset:21504
	ds_read_u16 v20, v86 offset:22528
	ds_read_u16 v26, v86 offset:23552
	ds_read_u16 v27, v86 offset:24576
	ds_read_u16 v43, v86 offset:25600
	ds_read_u16 v45, v86 offset:26624
	ds_read_u16 v47, v86 offset:27648
	s_waitcnt lgkmcnt(7)
	v_lshlrev_b32_e32 v11, 16, v0
	s_waitcnt lgkmcnt(5)
	v_lshlrev_b32_e32 v21, 16, v20
	v_lshlrev_b32_e32 v20, 16, v2
	v_pk_add_f32 v[22:23], v[20:21], 0 op_sel_hi:[1,0]
	v_pk_mov_b32 v[24:25], v[10:11], v[20:21] op_sel:[1,0]
	v_pk_add_f32 v[14:15], v[10:11], 0 op_sel_hi:[1,0]
	v_pk_add_f32 v[22:23], v[22:23], v[24:25]
	v_pk_mov_b32 v[18:19], v[16:17], v[10:11] op_sel:[1,0]
	v_pk_add_f32 v[22:23], v[22:23], v[10:11]
	v_pk_add_f32 v[14:15], v[14:15], v[18:19]
	v_pk_add_f32 v[18:19], v[22:23], v[18:19]
	s_waitcnt lgkmcnt(3)
	v_lshlrev_b32_e32 v23, 16, v27
	v_lshlrev_b32_e32 v22, 16, v26
	v_pk_add_f32 v[26:27], v[22:23], 0 op_sel_hi:[1,0]
	v_pk_mov_b32 v[50:51], v[20:21], v[22:23] op_sel:[1,0]
	ds_read_u16 v0, v86 offset:28672
	v_pk_add_f32 v[26:27], v[26:27], v[50:51]
	v_pk_add_f32 v[14:15], v[14:15], v[16:17]
	v_pk_add_f32 v[26:27], v[26:27], v[20:21]
	v_pk_add_f32 v[14:15], v[14:15], v[12:13]
	v_pk_add_f32 v[24:25], v[26:27], v[24:25]
	s_waitcnt lgkmcnt(2)
	v_lshlrev_b32_e32 v27, 16, v45
	v_lshlrev_b32_e32 v26, 16, v43
	v_pk_add_f32 v[52:53], v[26:27], 0 op_sel_hi:[1,0]
	v_pk_mov_b32 v[54:55], v[22:23], v[26:27] op_sel:[1,0]
	ds_read_u16 v2, v86 offset:30720
	ds_read_u16 v12, v86 offset:29696
	v_pk_add_f32 v[52:53], v[52:53], v[54:55]
	v_cndmask_b32_e32 v200, v201, v226, vcc
	v_pk_add_f32 v[52:53], v[52:53], v[22:23]
	v_cndmask_b32_e64 v7, v201, 0.5, vcc
	v_pk_add_f32 v[50:51], v[52:53], v[50:51]
	s_waitcnt lgkmcnt(2)
	v_lshlrev_b32_e32 v53, 16, v0
	v_lshlrev_b32_e32 v52, 16, v47
	v_pk_add_f32 v[56:57], v[52:53], 0 op_sel_hi:[1,0]
	v_pk_mov_b32 v[58:59], v[26:27], v[52:53] op_sel:[1,0]
	v_cndmask_b32_e64 v6, v201, 1.0, vcc
	v_pk_add_f32 v[56:57], v[56:57], v[58:59]
	s_mov_b32 s18, 0x3e800000
	v_pk_add_f32 v[56:57], v[56:57], v[26:27]
	v_pk_mul_f32 v[4:5], v[6:7], v[4:5]
	v_pk_add_f32 v[54:55], v[56:57], v[54:55]
	s_waitcnt lgkmcnt(0)
	v_lshlrev_b32_e32 v56, 16, v12
	v_lshlrev_b32_e32 v57, 16, v2
	v_pk_add_f32 v[76:77], v[56:57], 0 op_sel_hi:[1,0]
	v_pk_mov_b32 v[78:79], v[52:53], v[56:57] op_sel:[1,0]
	v_pk_mul_f32 v[6:7], v[18:19], s[18:19] op_sel_hi:[1,0]
	v_pk_add_f32 v[76:77], v[76:77], v[78:79]
	v_pk_mul_f32 v[54:55], v[54:55], s[18:19] op_sel_hi:[1,0]
	v_pk_add_f32 v[76:77], v[76:77], v[52:53]
	v_pk_mul_f32 v[50:51], v[50:51], s[18:19] op_sel_hi:[1,0]
	v_pk_add_f32 v[58:59], v[76:77], v[58:59]
	v_pk_mul_f32 v[76:77], v[200:201], v[8:9]
	v_pk_mul_f32 v[8:9], v[14:15], s[18:19] op_sel_hi:[1,0]
	v_pk_mul_f32 v[18:19], v[58:59], s[18:19] op_sel_hi:[1,0]
	v_pk_mul_f32 v[24:25], v[24:25], s[18:19] op_sel_hi:[1,0]
	v_sub_f32_e32 v14, v4, v1
	v_sub_f32_e32 v15, v5, v3
	v_sub_f32_e32 v4, v8, v10
	v_sub_f32_e32 v5, v9, v11
	v_sub_f32_e32 v0, v6, v20
	v_sub_f32_e32 v1, v7, v21
	v_sub_f32_e32 v10, v24, v22
	v_sub_f32_e32 v11, v25, v23
	v_sub_f32_e32 v8, v50, v26
	v_sub_f32_e32 v9, v51, v27
	v_sub_f32_e32 v2, v54, v52
	v_sub_f32_e32 v3, v55, v53
	v_sub_f32_e32 v6, v18, v56
	v_sub_f32_e32 v7, v19, v57
	v_sub_f32_e32 v12, v76, v13
	v_sub_f32_e32 v13, v77, v17

.LBB0_568:
	ds_read_u16 v0, v86 offset:8192
	s_cmp_eq_u32 s55, 0
	s_cselect_b64 vcc, -1, 0
	v_cndmask_b32_e64 v77, v203, 0.5, vcc
	v_cndmask_b32_e64 v76, v203, 1.0, vcc
	s_waitcnt lgkmcnt(0)
	v_lshlrev_b32_e32 v1, 16, v0
	ds_read_u16 v0, v86 offset:9216
	v_cndmask_b32_e32 v79, v203, v201, vcc
	v_cndmask_b32_e32 v78, v203, v226, vcc
	v_cndmask_b32_e32 v81, v203, v227, vcc
	v_cndmask_b32_e32 v80, v203, v228, vcc
	s_waitcnt lgkmcnt(0)
	v_lshlrev_b32_e32 v10, 16, v0
	ds_read_u16 v0, v86 offset:10240
	v_cndmask_b32_e32 v202, v203, v236, vcc
	s_waitcnt lgkmcnt(0)
	v_lshlrev_b32_e32 v11, 16, v0
	ds_read_u16 v0, v86 offset:11264
	s_waitcnt lgkmcnt(0)
	v_lshlrev_b32_e32 v8, 16, v0
	ds_read_u16 v0, v86 offset:12288
	s_waitcnt lgkmcnt(0)
	v_lshlrev_b32_e32 v9, 16, v0
	ds_read_u16 v0, v86 offset:13312
	v_pk_mov_b32 v[54:55], v[10:11], v[8:9] op_sel:[1,0]
	s_waitcnt lgkmcnt(0)
	v_lshlrev_b32_e32 v2, 16, v0
	ds_read_u16 v0, v86 offset:14336
	s_waitcnt lgkmcnt(0)
	v_lshlrev_b32_e32 v3, 16, v0
	ds_read_u16 v0, v86
	ds_read_u16 v4, v86 offset:1024
	s_waitcnt lgkmcnt(1)
	v_lshlrev_b32_e32 v14, 16, v0
	s_waitcnt lgkmcnt(0)
	v_lshlrev_b32_e32 v15, 16, v4
	ds_read_u16 v0, v86 offset:2048
	ds_read_u16 v4, v86 offset:3072
	v_mov_b32_e32 v24, v15
	s_waitcnt lgkmcnt(1)
	v_lshlrev_b32_e32 v25, 16, v0
	ds_read_u16 v0, v86 offset:4096
	s_waitcnt lgkmcnt(1)
	v_lshlrev_b32_e32 v12, 16, v4
	v_mov_b32_e32 v26, v25
	v_mov_b32_e32 v27, v12
	s_waitcnt lgkmcnt(0)
	v_lshlrev_b32_e32 v13, 16, v0
	ds_read_u16 v0, v86 offset:5120
	v_mov_b32_e32 v4, v13
	s_waitcnt lgkmcnt(0)
	v_lshlrev_b32_e32 v5, 16, v0
	ds_read_u16 v0, v86 offset:6144
	v_mov_b32_e32 v50, v5
	s_waitcnt lgkmcnt(0)
	v_lshlrev_b32_e32 v51, 16, v0
	ds_read_u16 v0, v86 offset:7168
	ds_read_u16 v6, v86 offset:15360
	ds_read_u16 v7, v86 offset:16384
	ds_read_u16 v16, v86 offset:17408
	ds_read_u16 v17, v86 offset:18432
	ds_read_u16 v18, v86 offset:19456
	ds_read_u16 v19, v86 offset:20480
	ds_read_u16 v20, v86 offset:21504
	ds_read_u16 v21, v86 offset:22528
	s_waitcnt lgkmcnt(7)
	v_lshlrev_b32_e32 v6, 16, v6
	s_waitcnt lgkmcnt(6)
	v_lshlrev_b32_e32 v7, 16, v7
	v_pk_add_f32 v[52:53], v[6:7], 0 op_sel_hi:[1,0]
	s_waitcnt lgkmcnt(1)
	v_lshlrev_b32_e32 v22, 16, v20
	s_waitcnt lgkmcnt(0)
	v_lshlrev_b32_e32 v23, 16, v21
	v_pk_mov_b32 v[20:21], v[2:3], v[6:7] op_sel:[1,0]
	v_lshlrev_b32_e32 v59, 16, v0
	v_pk_add_f32 v[52:53], v[52:53], v[20:21]
	v_mov_b32_e32 v0, v59
	v_pk_add_f32 v[98:99], v[52:53], v[2:3]
	v_pk_mov_b32 v[52:53], v[8:9], v[2:3] op_sel:[1,0]
	v_pk_mov_b32 v[56:57], v[0:1], v[10:11] op_sel:[1,0]
	v_pk_add_f32 v[98:99], v[98:99], v[52:53]
	v_mov_b32_e32 v58, v51
	v_pk_add_f32 v[98:99], v[98:99], v[8:9]
	v_lshlrev_b32_e32 v17, 16, v17
	v_pk_add_f32 v[98:99], v[98:99], v[54:55]
	v_lshlrev_b32_e32 v16, 16, v16
	v_pk_add_f32 v[98:99], v[98:99], v[10:11]
	v_lshlrev_b32_e32 v19, 16, v19
	v_pk_add_f32 v[98:99], v[98:99], v[56:57]
	v_lshlrev_b32_e32 v18, 16, v18
	v_pk_add_f32 v[98:99], v[98:99], v[0:1]
	ds_read_u16 v43, v86 offset:23552
	ds_read_u16 v45, v86 offset:24576
	v_pk_add_f32 v[98:99], v[98:99], v[58:59]
	s_nop 0
	v_pk_add_f32 v[98:99], v[98:99], v[50:51]
	s_nop 0
	v_pk_add_f32 v[98:99], v[98:99], v[4:5]
	s_nop 0
	v_pk_add_f32 v[98:99], v[98:99], v[12:13]
	s_nop 0
	v_pk_add_f32 v[98:99], v[98:99], v[26:27]
	s_nop 0
	v_pk_add_f32 v[24:25], v[98:99], v[24:25]
	v_cndmask_b32_e32 v99, v203, v234, vcc
	v_pk_add_f32 v[14:15], v[24:25], v[14:15]
	v_pk_mov_b32 v[24:25], v[6:7], v[16:17] op_sel:[1,0]
	v_pk_fma_f32 v[14:15], v[76:77], v[14:15], v[6:7] neg_lo:[0,0,1] neg_hi:[0,0,1]
	v_pk_add_f32 v[76:77], v[16:17], 0 op_sel_hi:[1,0]
	v_cndmask_b32_e32 v98, v203, v235, vcc
	v_pk_add_f32 v[76:77], v[76:77], v[24:25]
	s_nop 0
	v_pk_add_f32 v[76:77], v[76:77], v[6:7]
	s_nop 0
	v_pk_add_f32 v[76:77], v[76:77], v[20:21]
	s_nop 0
	v_pk_add_f32 v[76:77], v[76:77], v[2:3]
	s_nop 0
	v_pk_add_f32 v[76:77], v[76:77], v[52:53]
	s_nop 0
	v_pk_add_f32 v[76:77], v[76:77], v[8:9]
	s_nop 0
	v_pk_add_f32 v[76:77], v[76:77], v[54:55]
	s_nop 0
	v_pk_add_f32 v[76:77], v[76:77], v[10:11]
	s_nop 0
	v_pk_add_f32 v[76:77], v[76:77], v[56:57]
	s_nop 0
	v_pk_add_f32 v[76:77], v[76:77], v[0:1]
	s_nop 0
	v_pk_add_f32 v[76:77], v[76:77], v[58:59]
	s_nop 0
	v_pk_add_f32 v[76:77], v[76:77], v[50:51]
	s_nop 0
	v_pk_add_f32 v[76:77], v[76:77], v[4:5]
	s_nop 0
	v_pk_add_f32 v[12:13], v[76:77], v[12:13]
	v_pk_add_f32 v[76:77], v[18:19], 0 op_sel_hi:[1,0]
	v_pk_add_f32 v[12:13], v[12:13], v[26:27]
	v_pk_mov_b32 v[26:27], v[16:17], v[18:19] op_sel:[1,0]
	v_pk_fma_f32 v[12:13], v[78:79], v[12:13], v[16:17] neg_lo:[0,0,1] neg_hi:[0,0,1]
	v_pk_add_f32 v[76:77], v[76:77], v[26:27]
	s_nop 0
	v_pk_add_f32 v[76:77], v[76:77], v[16:17]
	s_nop 0
	v_pk_add_f32 v[76:77], v[76:77], v[24:25]
	s_nop 0
	v_pk_add_f32 v[76:77], v[76:77], v[6:7]
	s_nop 0
	v_pk_add_f32 v[76:77], v[76:77], v[20:21]
	s_nop 0
	v_pk_add_f32 v[76:77], v[76:77], v[2:3]
	s_nop 0
	v_pk_add_f32 v[76:77], v[76:77], v[52:53]
	s_nop 0
	v_pk_add_f32 v[76:77], v[76:77], v[8:9]
	s_nop 0
	v_pk_add_f32 v[76:77], v[76:77], v[54:55]
	s_nop 0
	v_pk_add_f32 v[76:77], v[76:77], v[10:11]
	s_nop 0
	v_pk_add_f32 v[76:77], v[76:77], v[56:57]
	s_nop 0
	v_pk_add_f32 v[76:77], v[76:77], v[0:1]
	s_nop 0
	v_pk_add_f32 v[76:77], v[76:77], v[58:59]
	s_nop 0
	v_pk_add_f32 v[50:51], v[76:77], v[50:51]
	v_pk_add_f32 v[76:77], v[22:23], 0 op_sel_hi:[1,0]
	v_pk_add_f32 v[4:5], v[50:51], v[4:5]
	v_pk_mov_b32 v[50:51], v[18:19], v[22:23] op_sel:[1,0]
	v_pk_fma_f32 v[4:5], v[80:81], v[4:5], v[18:19] neg_lo:[0,0,1] neg_hi:[0,0,1]
	v_pk_add_f32 v[76:77], v[76:77], v[50:51]
	s_nop 0
	v_pk_add_f32 v[76:77], v[76:77], v[18:19]
	s_nop 0
	v_pk_add_f32 v[76:77], v[76:77], v[26:27]
	s_nop 0
	v_pk_add_f32 v[76:77], v[76:77], v[16:17]
	s_nop 0
	v_pk_add_f32 v[76:77], v[76:77], v[24:25]
	s_nop 0
	v_pk_add_f32 v[76:77], v[76:77], v[6:7]
	s_nop 0
	v_pk_add_f32 v[76:77], v[76:77], v[20:21]
	s_nop 0
	v_pk_add_f32 v[76:77], v[76:77], v[2:3]
	s_nop 0
	v_pk_add_f32 v[76:77], v[76:77], v[52:53]
	s_nop 0
	v_pk_add_f32 v[76:77], v[76:77], v[8:9]
	s_nop 0
	v_pk_add_f32 v[76:77], v[76:77], v[54:55]
	s_nop 0
	v_pk_add_f32 v[76:77], v[76:77], v[10:11]
	s_nop 0
	v_pk_add_f32 v[76:77], v[76:77], v[56:57]
	s_nop 0
	v_pk_add_f32 v[0:1], v[76:77], v[0:1]
	s_nop 0
	v_pk_add_f32 v[0:1], v[0:1], v[58:59]
	v_cndmask_b32_e32 v59, v203, v199, vcc
	v_cndmask_b32_e32 v58, v203, v229, vcc
	v_pk_fma_f32 v[0:1], v[58:59], v[0:1], v[22:23] neg_lo:[0,0,1] neg_hi:[0,0,1]
	s_waitcnt lgkmcnt(0)
	v_lshlrev_b32_e32 v59, 16, v45
	v_lshlrev_b32_e32 v58, 16, v43
	v_pk_add_f32 v[78:79], v[58:59], 0 op_sel_hi:[1,0]
	v_pk_mov_b32 v[76:77], v[22:23], v[58:59] op_sel:[1,0]
	v_mov_b32_e32 v43, 0x3dcccccd
	v_pk_add_f32 v[78:79], v[78:79], v[76:77]
	s_nop 0
	v_pk_add_f32 v[78:79], v[78:79], v[22:23]
	s_nop 0
	v_pk_add_f32 v[78:79], v[78:79], v[50:51]
	s_nop 0
	v_pk_add_f32 v[78:79], v[78:79], v[18:19]
	s_nop 0
	v_pk_add_f32 v[78:79], v[78:79], v[26:27]
	s_nop 0
	v_pk_add_f32 v[78:79], v[78:79], v[16:17]
	s_nop 0
	v_pk_add_f32 v[78:79], v[78:79], v[24:25]
	s_nop 0
	v_pk_add_f32 v[78:79], v[78:79], v[6:7]
	s_nop 0
	v_pk_add_f32 v[78:79], v[78:79], v[20:21]
	s_nop 0
	v_pk_add_f32 v[78:79], v[78:79], v[2:3]
	s_nop 0
	v_pk_add_f32 v[78:79], v[78:79], v[52:53]
	s_nop 0
	v_pk_add_f32 v[78:79], v[78:79], v[8:9]
	s_nop 0
	v_pk_add_f32 v[78:79], v[78:79], v[54:55]
	s_nop 0
	v_pk_add_f32 v[10:11], v[78:79], v[10:11]
	s_nop 0
	v_pk_add_f32 v[10:11], v[10:11], v[56:57]
	v_cndmask_b32_e32 v57, v203, v43, vcc
	ds_read_u16 v43, v86 offset:25600
	ds_read_u16 v45, v86 offset:26624
	v_cndmask_b32_e32 v56, v203, v248, vcc
	v_pk_fma_f32 v[10:11], v[56:57], v[10:11], v[58:59] neg_lo:[0,0,1] neg_hi:[0,0,1]
	s_waitcnt lgkmcnt(1)
	v_lshlrev_b32_e32 v56, 16, v43
	s_waitcnt lgkmcnt(0)
	v_lshlrev_b32_e32 v57, 16, v45
	v_pk_add_f32 v[80:81], v[56:57], 0 op_sel_hi:[1,0]
	v_pk_mov_b32 v[78:79], v[58:59], v[56:57] op_sel:[1,0]
	ds_read_u16 v43, v86 offset:27648
	ds_read_u16 v45, v86 offset:28672
	v_pk_add_f32 v[80:81], v[80:81], v[78:79]
	s_nop 0
	v_pk_add_f32 v[80:81], v[80:81], v[58:59]
	s_nop 0
	v_pk_add_f32 v[80:81], v[80:81], v[76:77]
	s_nop 0
	v_pk_add_f32 v[80:81], v[80:81], v[22:23]
	s_nop 0
	v_pk_add_f32 v[80:81], v[80:81], v[50:51]
	s_nop 0
	v_pk_add_f32 v[80:81], v[80:81], v[18:19]
	s_nop 0
	v_pk_add_f32 v[80:81], v[80:81], v[26:27]
	s_nop 0
	v_pk_add_f32 v[80:81], v[80:81], v[16:17]
	s_nop 0
	v_pk_add_f32 v[80:81], v[80:81], v[24:25]
	s_nop 0
	v_pk_add_f32 v[80:81], v[80:81], v[6:7]
	s_nop 0
	v_pk_add_f32 v[80:81], v[80:81], v[20:21]
	s_nop 0
	v_pk_add_f32 v[80:81], v[80:81], v[2:3]
	s_nop 0
	v_pk_add_f32 v[80:81], v[80:81], v[52:53]
	s_nop 0
	v_pk_add_f32 v[8:9], v[80:81], v[8:9]
	s_nop 0
	v_pk_add_f32 v[8:9], v[8:9], v[54:55]
	v_cndmask_b32_e32 v55, v203, v225, vcc
	v_cndmask_b32_e32 v54, v203, v241, vcc
	v_pk_fma_f32 v[8:9], v[54:55], v[8:9], v[56:57] neg_lo:[0,0,1] neg_hi:[0,0,1]
	s_waitcnt lgkmcnt(0)
	v_lshlrev_b32_e32 v55, 16, v45
	v_lshlrev_b32_e32 v54, 16, v43
	v_pk_add_f32 v[100:101], v[54:55], 0 op_sel_hi:[1,0]
	v_pk_mov_b32 v[80:81], v[56:57], v[54:55] op_sel:[1,0]
	ds_read_u16 v43, v86 offset:30720
	ds_read_u16 v45, v86 offset:29696
	v_pk_add_f32 v[100:101], v[100:101], v[80:81]
	s_nop 0
	v_pk_add_f32 v[100:101], v[100:101], v[56:57]
	s_nop 0
	v_pk_add_f32 v[100:101], v[100:101], v[78:79]
	s_nop 0
	v_pk_add_f32 v[100:101], v[100:101], v[58:59]
	s_nop 0
	v_pk_add_f32 v[100:101], v[100:101], v[76:77]
	s_nop 0
	v_pk_add_f32 v[100:101], v[100:101], v[22:23]
	s_nop 0
	v_pk_add_f32 v[100:101], v[100:101], v[50:51]
	s_nop 0
	v_pk_add_f32 v[100:101], v[100:101], v[18:19]
	s_nop 0
	v_pk_add_f32 v[100:101], v[100:101], v[26:27]
	s_nop 0
	v_pk_add_f32 v[100:101], v[100:101], v[16:17]
	s_nop 0
	v_pk_add_f32 v[100:101], v[100:101], v[24:25]
	s_nop 0
	v_pk_add_f32 v[100:101], v[100:101], v[6:7]
	s_nop 0
	v_pk_add_f32 v[100:101], v[100:101], v[20:21]
	s_nop 0
	v_pk_add_f32 v[2:3], v[100:101], v[2:3]
	s_nop 0
	v_pk_add_f32 v[2:3], v[2:3], v[52:53]
	s_waitcnt lgkmcnt(0)
	v_lshlrev_b32_e32 v52, 16, v45
	v_lshlrev_b32_e32 v53, 16, v43
	v_pk_fma_f32 v[2:3], v[98:99], v[2:3], v[54:55] neg_lo:[0,0,1] neg_hi:[0,0,1]
	v_pk_add_f32 v[98:99], v[52:53], 0 op_sel_hi:[1,0]
	v_pk_mov_b32 v[100:101], v[54:55], v[52:53] op_sel:[1,0]
	s_nop 0
	v_pk_add_f32 v[98:99], v[98:99], v[100:101]
	s_nop 0
	v_pk_add_f32 v[54:55], v[98:99], v[54:55]
	s_nop 0
	v_pk_add_f32 v[54:55], v[54:55], v[80:81]
	s_nop 0
	v_pk_add_f32 v[54:55], v[54:55], v[56:57]
	s_nop 0
	v_pk_add_f32 v[54:55], v[54:55], v[78:79]
	s_nop 0
	v_pk_add_f32 v[54:55], v[54:55], v[58:59]
	s_nop 0
	v_pk_add_f32 v[54:55], v[54:55], v[76:77]
	s_nop 0
	v_pk_add_f32 v[22:23], v[54:55], v[22:23]
	s_nop 0
	v_pk_add_f32 v[22:23], v[22:23], v[50:51]
	s_nop 0
	v_pk_add_f32 v[18:19], v[22:23], v[18:19]
	s_nop 0
	v_pk_add_f32 v[18:19], v[18:19], v[26:27]
	s_nop 0
	v_pk_add_f32 v[16:17], v[18:19], v[16:17]
	s_nop 0
	v_pk_add_f32 v[16:17], v[16:17], v[24:25]
	s_nop 0
	v_pk_add_f32 v[6:7], v[16:17], v[6:7]
	s_nop 0
	v_pk_add_f32 v[6:7], v[6:7], v[20:21]
	s_nop 0
	v_pk_fma_f32 v[6:7], v[202:203], v[6:7], v[52:53] neg_lo:[0,0,1] neg_hi:[0,0,1]
	s_cbranch_execz .LBB0_561
	s_branch .LBB0_562
